# RWKV post: partial-y reads issued right after the barrier, reduce + atomic after commit and step B (LDS latency hidden)
# speedup vs baseline: 1.0024x; 1.0024x over previous
.Lrs_post:
	v_mov_b64_e32 v[56:57], v[82:83]
	s_waitcnt lgkmcnt(0)
	s_barrier
	ds_read_b128 v[186:189], v101
	ds_read_b128 v[190:193], v101 offset:16
	ds_read_b128 v[194:197], v101 offset:32
	ds_read_b128 v[198:201], v101 offset:48
	s_andn2_b64 vcc, exec, s[28:29]
	s_cbranch_vccnz .Lrp_last
	s_waitcnt vmcnt(0)
	v_lshlrev_b32_e32 v60, 16, v20
	v_and_b32_e32 v61, 0xffff0000, v20
	v_lshlrev_b32_e32 v62, 16, v21
	v_and_b32_e32 v63, 0xffff0000, v21
	v_lshlrev_b32_e32 v64, 16, v22
	v_and_b32_e32 v65, 0xffff0000, v22
	v_lshlrev_b32_e32 v66, 16, v23
	v_and_b32_e32 v67, 0xffff0000, v23
	ds_write_b128 v149, v[60:63]
	ds_write_b128 v149, v[64:67] offset:16
	v_lshlrev_b32_e32 v162, 16, v52
	v_and_b32_e32 v163, 0xffff0000, v52
	v_lshlrev_b32_e32 v164, 16, v53
	v_and_b32_e32 v165, 0xffff0000, v53
	v_lshlrev_b32_e32 v166, 16, v54
	v_and_b32_e32 v167, 0xffff0000, v54
	v_lshlrev_b32_e32 v168, 16, v55
	v_and_b32_e32 v169, 0xffff0000, v55
	ds_write_b128 v150, v[162:165]
	ds_write_b128 v150, v[166:169] offset:16
	s_and_saveexec_b64 s[26:27], s[14:15]
	s_cbranch_execz .Lrc_skip
	v_lshlrev_b32_e32 v60, 16, v48
	v_and_b32_e32 v61, 0xffff0000, v48
	v_lshlrev_b32_e32 v62, 16, v49
	v_and_b32_e32 v63, 0xffff0000, v49
	v_lshlrev_b32_e32 v64, 16, v50
	v_and_b32_e32 v65, 0xffff0000, v50
	v_lshlrev_b32_e32 v66, 16, v51
	v_and_b32_e32 v67, 0xffff0000, v51
	ds_write_b128 v151, v[60:63]
	ds_write_b128 v151, v[64:67] offset:16

.Lrb2_done:
	s_waitcnt lgkmcnt(12)
	s_branch .Lrp_red

.Lrp_red:
	v_add_u32_e32 v202, s35, v90
	v_ashrrev_i32_e32 v203, 31, v202
	v_lshlrev_b64 v[202:203], 10, v[202:203]
	v_lshl_add_u64 v[202:203], v[102:103], 0, v[202:203]
	v_add_f32_e32 v186, v186, v187
	v_add_f32_e32 v188, v188, v189
	v_add_f32_e32 v190, v190, v191
	v_add_f32_e32 v192, v192, v193
	v_add_f32_e32 v186, v186, v188
	v_add_f32_e32 v190, v190, v192
	v_add_f32_e32 v194, v194, v195
	v_add_f32_e32 v196, v196, v197
	v_add_f32_e32 v198, v198, v199
	v_add_f32_e32 v200, v200, v201
	v_add_f32_e32 v194, v194, v196
	v_add_f32_e32 v198, v198, v200
	v_add_f32_e32 v186, v186, v190
	v_add_f32_e32 v194, v194, v198
	v_add_f32_e32 v186, v186, v194
	s_nop 1
	v_mov_b32_dpp v187, v186 quad_perm:[1,0,3,2] row_mask:0xf bank_mask:0xf bound_ctrl:1
	s_nop 0
	v_cvt_pk_bf16_f32 v16, v186, v187
	s_mov_b32 s26, 0x55555555
	s_mov_b32 s27, 0x55555555
	s_and_b64 exec, exec, s[26:27]
	global_atomic_pk_add_bf16 v[202:203], v16, off
	s_mov_b64 exec, -1
	s_branch .LBB0_423
